# kv-latent row pass: gain-vector load moved to the iteration header (spare regs), rope table load issued at the top of the tail block with a counted vmcnt(2)
# speedup vs baseline: 1.0032x; 1.0032x over previous
; DI int get_bid() { int b = blockIdx.x; asm volatile("" : "+s"(b)); return b; }
; DI u16 f2bf(float x) { unsigned u = __float_as_uint(x); u += 0x7fffu + ((u >> 16) & 1u); return (u16)(u >> 16); }
; DI unsigned pk2(float a, float b) { f32x2_t f = {a, b}; return __builtin_bit_cast(unsigned, __builtin_convertvector(f, bf16x2_t)); }
; DI void odd_rows(const Params& p, int o) {
;     ...
;   for (int r = get_bid() * 4 + (tid >> 6); r < M_TOK; r += gridDim.x * 4) {
;     const float* z = zq + (size_t)r * 704;
;     float2 qv[3]; float ss = 0.f;
; #pragma unroll
;     for (int i = 0; i < 3; ++i) { qv[i] = *(const float2*)(z + lane * 2 + 128 * i); ss += qv[i].x * qv[i].x + qv[i].y * qv[i].y; }
;     const float4 kv = *(const float4*)(z + 384 + lane * 4);
;     float sk = kv.x * kv.x + kv.y * kv.y + kv.z * kv.z + kv.w * kv.w;
;     const float kr = z[640 + lane];
;     ss = wave_sum(ss); sk = wave_sum(sk);
;     const float rq = rsqrtf(ss * (1.f / 384.f) + 1e-6f);
;     const float rk = rsqrtf(sk * (1.f / 256.f) + 1e-6f);
; #pragma unroll
;     for (int i = 0; i < 3; ++i) {
;       const float2 w = *(const float2*)(qnw + lane * 2 + 128 * i);
;       *(unsigned*)(qn + (size_t)r * 384 + lane * 2 + 128 * i) = pk2(qv[i].x * rq * w.x, qv[i].y * rq * w.y);
;     }
;     size_t kvrow; float *dck, *dkr; int pos;
;     if (r < M_PROMPT) {
;       kvrow = r; pos = r & 8191;
;       dck = p.out + OUT_CKVP + ((size_t)o * 16384 + r) * 256;
;       dkr = p.out + OUT_KRP + ((size_t)o * 16384 + r) * 64;
;     } else {
;       const int rr = r - M_PROMPT, b = rr >> 5, s = rr & 31;
;       kvrow = (size_t)M_PROMPT + b * KSTR_S + 1024 + s; pos = 1024 + s;
;       dck = p.out + OUT_CKVS + ((size_t)o * 512 + rr) * 256;
;       dkr = p.out + OUT_KRS + ((size_t)o * 512 + rr) * 64;
;     }
;     const float4 w4 = *(const float4*)(kvw + lane * 4);
;     const float c0 = kv.x * rk * w4.x, c1 = kv.y * rk * w4.y, c2 = kv.z * rk * w4.z, c3 = kv.w * rk * w4.w;
;     *(float4*)(dck + lane * 4) = make_float4(c0, c1, c2, c3);
;     st_bf4(ckvb + kvrow * 256 + lane * 4, c0, c1, c2, c3);
;     const float other = __shfl_xor(kr, 32, 64);
;     const float2 cs = rope[pos * 32 + (lane & 31)];
;     const float ro = lane < 32 ? kr * cs.x - other * cs.y : kr * cs.x + other * cs.y;
;     dkr[lane] = ro;
;     krb[kvrow * 64 + lane] = f2bf(ro);
.LBB0_118:
	s_or_b64 exec, exec, s[40:41]
	v_lshl_or_b32 v172, v27, 5, v9
	v_mov_b32_e32 v173, v183
	v_lshl_add_u64 v[172:173], v[172:173], 3, s[82:83]
	global_load_dwordx2 v[174:175], v[172:173], off
	v_mul_f32_e32 v7, 0x4b800000, v26
	v_cndmask_b32_e64 v7, v26, v7, s[38:39]
	v_rsq_f32_e32 v7, v7
	v_readlane_b32 s4, v255, 5
	v_readlane_b32 s6, v255, 7
	v_readlane_b32 s7, v255, 8
	v_mul_f32_e32 v25, 0x45800000, v7
	v_cndmask_b32_e64 v26, v7, v25, s[38:39]
	v_lshl_add_u64 v[32:33], s[6:7], 0, v[32:33]
	v_lshlrev_b64 v[40:41], 10, v[28:29]
	v_lshl_add_u64 v[30:31], s[6:7], 0, v[30:31]
	v_lshlrev_b64 v[28:29], 8, v[28:29]
	v_lshl_add_u64 v[32:33], v[32:33], 0, v[40:41]
	v_lshl_add_u64 v[28:29], v[30:31], 0, v[28:29]
	v_pk_mul_f32 v[30:31], v[2:3], v[26:27] op_sel_hi:[1,0]
	v_pk_mul_f32 v[40:41], v[4:5], v[26:27] op_sel_hi:[1,0]
	v_mov_b32_e32 v25, v183
	v_lshl_add_u64 v[24:25], v[32:33], 0, v[24:25]
	v_add_u32_e32 v6, s3, v6
	v_cmp_lt_i32_e64 s[38:39], s64, v6
	s_or_b64 s[44:45], s[38:39], s[44:45]
	v_readlane_b32 s5, v255, 6
	v_readlane_b32 s8, v255, 9
	v_readlane_b32 s9, v255, 10
	v_readlane_b32 s10, v255, 11
	v_readlane_b32 s11, v255, 12
	v_pk_mul_f32 v[2:3], v[30:31], v[168:169]
	v_pk_mul_f32 v[4:5], v[40:41], v[170:171]
	global_store_dwordx4 v[24:25], v[2:5], off
	v_lshlrev_b64 v[24:25], 9, v[22:23]
	v_lshl_add_u64 v[24:25], v[16:17], 0, v[24:25]
	v_cvt_pk_bf16_f32 v2, v2, v3
	v_cvt_pk_bf16_f32 v3, v4, v5
	global_store_dwordx2 v[24:25], v[2:3], off
	ds_bpermute_b32 v4, v34, v21
	s_waitcnt vmcnt(2) lgkmcnt(0)
	v_mul_f32_e32 v3, v175, v4
	v_cndmask_b32_e64 v4, v3, -v3, vcc
	v_fmac_f32_e32 v4, v21, v174
	v_mov_b32_e32 v21, v183
	v_lshl_add_u64 v[2:3], v[28:29], 0, v[20:21]
	global_store_dword v[2:3], v4, off
	v_bfe_u32 v2, v4, 16, 1
	v_add3_u32 v4, v4, v2, s86
	v_lshlrev_b64 v[2:3], 7, v[22:23]
	v_lshl_add_u64 v[2:3], v[18:19], 0, v[2:3]
	global_store_short_d16_hi v[2:3], v4, off
	s_andn2_b64 exec, exec, s[44:45]
	s_cbranch_execz .LBB0_123
.LBB0_119:
	global_load_dwordx4 v[168:171], v[14:15], off offset:1024
	global_load_dwordx2 v[100:101], v[10:11], off offset:1536
	global_load_dwordx2 v[102:103], v[10:11], off offset:2048
	global_load_dwordx2 v[104:105], v[10:11], off offset:2560
	v_mov_b64_e32 v[2:3], s[84:85]
	s_movk_i32 s4, 0xb00
	v_mad_i64_i32 v[22:23], s[4:5], v6, s4, v[2:3]
	v_lshlrev_b32_e32 v24, 2, v8
	v_mov_b32_e32 v25, v183
	v_lshl_add_u64 v[2:3], v[22:23], 0, v[24:25]
	v_lshl_add_u64 v[26:27], v[22:23], 0, v[182:183]
	global_load_dwordx4 v[2:5], v[2:3], off offset:1536
	s_nop 0
	global_load_dwordx2 v[28:29], v[26:27], off offset:512
	global_load_dwordx2 v[30:31], v[26:27], off
	global_load_dwordx2 v[32:33], v[26:27], off offset:1024
	s_nop 0
	v_mov_b32_e32 v21, v183
	v_lshl_add_u64 v[22:23], v[22:23], 0, v[20:21]
	global_load_dword v21, v[22:23], off offset:2560
	s_mov_b32 s4, 0x3b800000
	s_mov_b32 s5, 0x3b2aaaab
	s_waitcnt vmcnt(6)
	s_waitcnt vmcnt(3)
	v_pk_mul_f32 v[42:43], v[28:29], v[28:29]
	s_waitcnt vmcnt(5)
	s_waitcnt vmcnt(2)
	v_mov_b32_e32 v46, v31
	s_waitcnt vmcnt(4)
	s_waitcnt vmcnt(1)
	v_mov_b32_e32 v47, v33
	v_pk_mul_f32 v[22:23], v[2:3], v[2:3]
	v_mov_b32_e32 v44, v30
	v_mov_b32_e32 v45, v32
	v_pk_mul_f32 v[46:47], v[46:47], v[46:47]
	v_pk_mul_f32 v[26:27], v[4:5], v[4:5]
	v_mov_b32_e32 v48, v22
	v_mov_b32_e32 v49, v42
	v_mov_b32_e32 v42, v23
	v_pk_fma_f32 v[44:45], v[44:45], v[44:45], v[46:47]
	v_mov_b32_e32 v22, v26
	v_pk_add_f32 v[42:43], v[48:49], v[42:43]
	v_mov_b32_e32 v23, v44
	v_mov_b32_e32 v44, v27
	v_pk_add_f32 v[22:23], v[42:43], v[22:23]
	s_nop 0
	v_pk_add_f32 v[22:23], v[22:23], v[44:45]
	v_mov_b32_e32 v26, v22
	v_mov_b32_e32 v27, v23
	s_nop 1
	v_permlane32_swap_b32_e32 v22, v26
	v_permlane32_swap_b32_e32 v23, v27
	s_waitcnt lgkmcnt(0)
	v_pk_add_f32 v[22:23], v[22:23], v[26:27]
	v_mov_b32_e32 v26, v22
	v_mov_b32_e32 v27, v23
	s_nop 1
	v_permlane16_swap_b32_e32 v22, v26
	v_permlane16_swap_b32_e32 v23, v27
	s_waitcnt lgkmcnt(0)
	v_pk_add_f32 v[22:23], v[22:23], v[26:27]
	s_nop 1
	v_mov_b32_dpp v26, v22 row_ror:8 row_mask:0xf bank_mask:0xf
	v_mov_b32_dpp v27, v23 row_ror:8 row_mask:0xf bank_mask:0xf
	s_waitcnt lgkmcnt(0)
	v_pk_add_f32 v[22:23], v[22:23], v[26:27]
	s_nop 1
	v_mov_b32_dpp v26, v22 row_ror:4 row_mask:0xf bank_mask:0xf
	v_mov_b32_dpp v27, v23 row_ror:4 row_mask:0xf bank_mask:0xf
	s_waitcnt lgkmcnt(0)
	v_pk_add_f32 v[22:23], v[22:23], v[26:27]
	s_nop 1
	v_mov_b32_dpp v26, v22 quad_perm:[2,3,0,1] row_mask:0xf bank_mask:0xf
	v_mov_b32_dpp v27, v23 quad_perm:[2,3,0,1] row_mask:0xf bank_mask:0xf
	s_waitcnt lgkmcnt(0)
	v_pk_add_f32 v[22:23], v[22:23], v[26:27]
	s_nop 1
	v_mov_b32_dpp v26, v22 quad_perm:[1,0,3,2] row_mask:0xf bank_mask:0xf
	v_mov_b32_dpp v27, v23 quad_perm:[1,0,3,2] row_mask:0xf bank_mask:0xf
	s_waitcnt lgkmcnt(0)
	v_pk_add_f32 v[22:23], v[22:23], v[26:27]
	s_nop 0
	v_pk_fma_f32 v[26:27], v[22:23], s[4:5], v[184:185] op_sel_hi:[1,1,0]
	s_movk_i32 s4, 0x300
	v_mul_f32_e32 v7, 0x4b800000, v27
	v_cmp_gt_f32_e64 s[38:39], s33, v27
	v_mad_i64_i32 v[22:23], s[4:5], v6, s4, v[12:13]
	s_nop 0
	v_cndmask_b32_e64 v7, v27, v7, s[38:39]
	v_rsq_f32_e32 v7, v7
	s_movk_i32 s4, 0x3fff
	v_cmp_lt_i32_e64 s[40:41], s4, v6
	v_mul_f32_e32 v25, 0x45800000, v7
	v_cndmask_b32_e64 v42, v7, v25, s[38:39]
	v_pk_mul_f32 v[30:31], v[30:31], v[42:43] op_sel_hi:[1,0]
	v_pk_mul_f32 v[28:29], v[28:29], v[42:43] op_sel_hi:[1,0]
	s_waitcnt vmcnt(3)
	v_pk_mul_f32 v[30:31], v[100:101], v[30:31]
	v_cmp_gt_f32_e64 s[38:39], s33, v26
	v_cvt_pk_bf16_f32 v7, v30, v31
	global_store_dword v[22:23], v7, off
	s_nop 0
	s_waitcnt vmcnt(1)
	v_pk_mul_f32 v[28:29], v[102:103], v[28:29]
	s_nop 0
	v_cvt_pk_bf16_f32 v7, v28, v29
	global_store_dword v[22:23], v7, off offset:256
	s_nop 0
	v_pk_mul_f32 v[30:31], v[32:33], v[42:43] op_sel_hi:[1,0]
	v_ashrrev_i32_e32 v7, 31, v6
	s_waitcnt vmcnt(0)
	v_pk_mul_f32 v[28:29], v[30:31], v[104:105]
	s_nop 0
	v_cvt_pk_bf16_f32 v25, v28, v29
	global_store_dword v[22:23], v25, off offset:512
	v_mov_b32_e32 v40, v100
	v_mov_b32_e32 v41, v101
	s_and_saveexec_b64 s[4:5], s[40:41]
	s_xor_b64 s[40:41], exec, s[4:5]
	s_cbranch_execz .LBB0_121
	v_add_u32_e32 v22, 0xffffc000, v6
	v_lshrrev_b32_e32 v22, 5, v22
	s_movk_i32 s4, 0x480
	v_and_b32_e32 v25, 31, v6
	v_mul_lo_u32 v22, v22, s4
	s_movk_i32 s4, 0xc200
	v_or_b32_e32 v22, v22, v25
	s_mov_b32 s5, -1
	v_add_u32_e32 v22, 0x4400, v22
	v_mov_b32_e32 v23, v183
	v_or_b32_e32 v27, 0x400, v25
	v_lshl_add_u64 v[28:29], v[6:7], 0, s[4:5]

; DI int get_bid() { int b = blockIdx.x; asm volatile("" : "+s"(b)); return b; }
; DI u16 f2bf(float x) { unsigned u = __float_as_uint(x); u += 0x7fffu + ((u >> 16) & 1u); return (u16)(u >> 16); }
; DI unsigned pk2(float a, float b) { f32x2_t f = {a, b}; return __builtin_bit_cast(unsigned, __builtin_convertvector(f, bf16x2_t)); }
; DI void odd_rows(const Params& p, int o) {
;     ...
;   for (int r = get_bid() * 4 + (tid >> 6); r < M_TOK; r += gridDim.x * 4) {
;     const float* z = zq + (size_t)r * 704;
;     float2 qv[3]; float ss = 0.f;
; #pragma unroll
;     for (int i = 0; i < 3; ++i) { qv[i] = *(const float2*)(z + lane * 2 + 128 * i); ss += qv[i].x * qv[i].x + qv[i].y * qv[i].y; }
;     const float4 kv = *(const float4*)(z + 384 + lane * 4);
;     float sk = kv.x * kv.x + kv.y * kv.y + kv.z * kv.z + kv.w * kv.w;
;     const float kr = z[640 + lane];
;     ss = wave_sum(ss); sk = wave_sum(sk);
;     const float rq = rsqrtf(ss * (1.f / 384.f) + 1e-6f);
;     const float rk = rsqrtf(sk * (1.f / 256.f) + 1e-6f);
; #pragma unroll
;     for (int i = 0; i < 3; ++i) {
;       const float2 w = *(const float2*)(qnw + lane * 2 + 128 * i);
;       *(unsigned*)(qn + (size_t)r * 384 + lane * 2 + 128 * i) = pk2(qv[i].x * rq * w.x, qv[i].y * rq * w.y);
;     }
;     size_t kvrow; float *dck, *dkr; int pos;
;     if (r < M_PROMPT) {
;       kvrow = r; pos = r & 8191;
;       dck = p.out + OUT_CKVP + ((size_t)o * 16384 + r) * 256;
;       dkr = p.out + OUT_KRP + ((size_t)o * 16384 + r) * 64;
;     } else {
;       const int rr = r - M_PROMPT, b = rr >> 5, s = rr & 31;
;       kvrow = (size_t)M_PROMPT + b * KSTR_S + 1024 + s; pos = 1024 + s;
;       dck = p.out + OUT_CKVS + ((size_t)o * 512 + rr) * 256;
;       dkr = p.out + OUT_KRS + ((size_t)o * 512 + rr) * 64;
;     }
;     const float4 w4 = *(const float4*)(kvw + lane * 4);
;     const float c0 = kv.x * rk * w4.x, c1 = kv.y * rk * w4.y, c2 = kv.z * rk * w4.z, c3 = kv.w * rk * w4.w;
;     *(float4*)(dck + lane * 4) = make_float4(c0, c1, c2, c3);
;     st_bf4(ckvb + kvrow * 256 + lane * 4, c0, c1, c2, c3);
;     const float other = __shfl_xor(kr, 32, 64);
;     const float2 cs = rope[pos * 32 + (lane & 31)];
;     const float ro = lane < 32 ? kr * cs.x - other * cs.y : kr * cs.x + other * cs.y;
;     dkr[lane] = ro;
;     krb[kvrow * 64 + lane] = f2bf(ro);
.LBB0_1000:
	s_or_b64 exec, exec, s[40:41]
	v_lshl_or_b32 v172, v25, 5, v7
	v_mov_b32_e32 v173, v183
	v_lshl_add_u64 v[172:173], v[172:173], 3, s[82:83]
	global_load_dwordx2 v[174:175], v[172:173], off
	v_mul_f32_e32 v5, 0x4b800000, v24
	v_cndmask_b32_e64 v5, v24, v5, s[38:39]
	v_rsq_f32_e32 v5, v5
	v_readlane_b32 s4, v255, 5
	v_readlane_b32 s6, v255, 7
	v_readlane_b32 s7, v255, 8
	v_mul_f32_e32 v23, 0x45800000, v5
	v_cndmask_b32_e64 v24, v5, v23, s[38:39]
	v_lshl_add_u64 v[30:31], s[6:7], 0, v[30:31]
	v_lshlrev_b64 v[40:41], 10, v[26:27]
	v_lshl_add_u64 v[28:29], s[6:7], 0, v[28:29]
	v_lshlrev_b64 v[26:27], 8, v[26:27]
	v_lshl_add_u64 v[30:31], v[30:31], 0, v[40:41]
	v_lshl_add_u64 v[26:27], v[28:29], 0, v[26:27]
	v_pk_mul_f32 v[28:29], v[0:1], v[24:25] op_sel_hi:[1,0]
	v_pk_mul_f32 v[40:41], v[2:3], v[24:25] op_sel_hi:[1,0]
	v_mov_b32_e32 v23, v183
	v_lshl_add_u64 v[22:23], v[30:31], 0, v[22:23]
	v_add_u32_e32 v4, s3, v4
	v_cmp_lt_i32_e64 s[38:39], s64, v4
	s_or_b64 s[44:45], s[38:39], s[44:45]
	v_readlane_b32 s5, v255, 6
	v_readlane_b32 s8, v255, 9
	v_readlane_b32 s9, v255, 10
	v_readlane_b32 s10, v255, 11
	v_readlane_b32 s11, v255, 12
	v_pk_mul_f32 v[0:1], v[28:29], v[168:169]
	v_pk_mul_f32 v[2:3], v[40:41], v[170:171]
	global_store_dwordx4 v[22:23], v[0:3], off
	v_lshlrev_b64 v[22:23], 9, v[20:21]
	v_lshl_add_u64 v[22:23], v[14:15], 0, v[22:23]
	v_cvt_pk_bf16_f32 v0, v0, v1
	v_cvt_pk_bf16_f32 v1, v2, v3
	global_store_dwordx2 v[22:23], v[0:1], off
	ds_bpermute_b32 v2, v33, v19
	s_waitcnt vmcnt(2) lgkmcnt(0)
	v_mul_f32_e32 v1, v175, v2
	v_cndmask_b32_e64 v2, v1, -v1, vcc
	v_fmac_f32_e32 v2, v19, v174
	v_mov_b32_e32 v19, v183
	v_lshl_add_u64 v[0:1], v[26:27], 0, v[18:19]
	global_store_dword v[0:1], v2, off
	v_bfe_u32 v0, v2, 16, 1
	v_add3_u32 v2, v2, v0, s86
	v_lshlrev_b64 v[0:1], 7, v[20:21]
	v_lshl_add_u64 v[0:1], v[16:17], 0, v[0:1]
	global_store_short_d16_hi v[0:1], v2, off
	s_andn2_b64 exec, exec, s[44:45]
	s_cbranch_execz .LBB0_1005
.LBB0_1001:
	global_load_dwordx4 v[168:171], v[12:13], off
	global_load_dwordx2 v[100:101], v[8:9], off
	global_load_dwordx2 v[102:103], v[8:9], off offset:512
	global_load_dwordx2 v[104:105], v[8:9], off offset:1024
	v_mov_b64_e32 v[0:1], s[84:85]
	s_movk_i32 s4, 0xb00
	v_mad_i64_i32 v[20:21], s[4:5], v4, s4, v[0:1]
	v_lshlrev_b32_e32 v22, 2, v6
	v_mov_b32_e32 v23, v183
	v_lshl_add_u64 v[0:1], v[20:21], 0, v[22:23]
	v_lshl_add_u64 v[24:25], v[20:21], 0, v[182:183]
	global_load_dwordx4 v[0:3], v[0:1], off offset:1536
	s_nop 0
	global_load_dwordx2 v[26:27], v[24:25], off offset:512
	global_load_dwordx2 v[28:29], v[24:25], off
	global_load_dwordx2 v[30:31], v[24:25], off offset:1024
	s_nop 0
	v_mov_b32_e32 v19, v183
	v_lshl_add_u64 v[20:21], v[20:21], 0, v[18:19]
	global_load_dword v19, v[20:21], off offset:2560
	s_mov_b32 s4, 0x3b800000
	s_mov_b32 s5, 0x3b2aaaab
	s_waitcnt vmcnt(6)
	s_waitcnt vmcnt(3)
	v_pk_mul_f32 v[42:43], v[26:27], v[26:27]
	s_waitcnt vmcnt(5)
	s_waitcnt vmcnt(2)
	v_mov_b32_e32 v46, v29
	s_waitcnt vmcnt(4)
	s_waitcnt vmcnt(1)
	v_mov_b32_e32 v47, v31
	v_pk_mul_f32 v[20:21], v[0:1], v[0:1]
	v_mov_b32_e32 v44, v28
	v_mov_b32_e32 v45, v30
	v_pk_mul_f32 v[46:47], v[46:47], v[46:47]
	v_pk_mul_f32 v[24:25], v[2:3], v[2:3]
	v_mov_b32_e32 v48, v20
	v_mov_b32_e32 v49, v42
	v_mov_b32_e32 v42, v21
	v_pk_fma_f32 v[44:45], v[44:45], v[44:45], v[46:47]
	v_mov_b32_e32 v20, v24
	v_pk_add_f32 v[42:43], v[48:49], v[42:43]
	v_mov_b32_e32 v21, v44
	v_mov_b32_e32 v44, v25
	v_pk_add_f32 v[20:21], v[42:43], v[20:21]
	s_nop 0
	v_pk_add_f32 v[20:21], v[20:21], v[44:45]
	v_mov_b32_e32 v24, v20
	v_mov_b32_e32 v25, v21
	s_nop 1
	v_permlane32_swap_b32_e32 v20, v24
	v_permlane32_swap_b32_e32 v21, v25
	s_waitcnt lgkmcnt(0)
	v_pk_add_f32 v[20:21], v[20:21], v[24:25]
	v_mov_b32_e32 v24, v20
	v_mov_b32_e32 v25, v21
	s_nop 1
	v_permlane16_swap_b32_e32 v20, v24
	v_permlane16_swap_b32_e32 v21, v25
	s_waitcnt lgkmcnt(0)
	v_pk_add_f32 v[20:21], v[20:21], v[24:25]
	s_nop 1
	v_mov_b32_dpp v24, v20 row_ror:8 row_mask:0xf bank_mask:0xf
	v_mov_b32_dpp v25, v21 row_ror:8 row_mask:0xf bank_mask:0xf
	s_waitcnt lgkmcnt(0)
	v_pk_add_f32 v[20:21], v[20:21], v[24:25]
	s_nop 1
	v_mov_b32_dpp v24, v20 row_ror:4 row_mask:0xf bank_mask:0xf
	v_mov_b32_dpp v25, v21 row_ror:4 row_mask:0xf bank_mask:0xf
	s_waitcnt lgkmcnt(0)
	v_pk_add_f32 v[20:21], v[20:21], v[24:25]
	s_nop 1
	v_mov_b32_dpp v24, v20 quad_perm:[2,3,0,1] row_mask:0xf bank_mask:0xf
	v_mov_b32_dpp v25, v21 quad_perm:[2,3,0,1] row_mask:0xf bank_mask:0xf
	s_waitcnt lgkmcnt(0)
	v_pk_add_f32 v[20:21], v[20:21], v[24:25]
	s_nop 1
	v_mov_b32_dpp v24, v20 quad_perm:[1,0,3,2] row_mask:0xf bank_mask:0xf
	v_mov_b32_dpp v25, v21 quad_perm:[1,0,3,2] row_mask:0xf bank_mask:0xf
	s_waitcnt lgkmcnt(0)
	v_pk_add_f32 v[20:21], v[20:21], v[24:25]
	s_nop 0
	v_pk_fma_f32 v[24:25], v[20:21], s[4:5], v[184:185] op_sel_hi:[1,1,0]
	s_movk_i32 s4, 0x300
	v_mul_f32_e32 v5, 0x4b800000, v25
	v_cmp_gt_f32_e64 s[38:39], s33, v25
	v_mad_i64_i32 v[20:21], s[4:5], v4, s4, v[10:11]
	s_nop 0
	v_cndmask_b32_e64 v5, v25, v5, s[38:39]
	v_rsq_f32_e32 v5, v5
	s_movk_i32 s4, 0x3fff
	v_cmp_lt_i32_e64 s[40:41], s4, v4
	v_mul_f32_e32 v23, 0x45800000, v5
	v_cndmask_b32_e64 v42, v5, v23, s[38:39]
	v_pk_mul_f32 v[28:29], v[28:29], v[42:43] op_sel_hi:[1,0]
	v_pk_mul_f32 v[26:27], v[26:27], v[42:43] op_sel_hi:[1,0]
	s_waitcnt vmcnt(3)
	v_pk_mul_f32 v[28:29], v[100:101], v[28:29]
	v_cmp_gt_f32_e64 s[38:39], s33, v24
	v_cvt_pk_bf16_f32 v5, v28, v29
	global_store_dword v[20:21], v5, off
	s_nop 0
	s_waitcnt vmcnt(1)
	v_pk_mul_f32 v[26:27], v[102:103], v[26:27]
	s_nop 0
	v_cvt_pk_bf16_f32 v5, v26, v27
	global_store_dword v[20:21], v5, off offset:256
	s_nop 0
	v_pk_mul_f32 v[28:29], v[30:31], v[42:43] op_sel_hi:[1,0]
	v_ashrrev_i32_e32 v5, 31, v4
	s_waitcnt vmcnt(0)
	v_pk_mul_f32 v[26:27], v[28:29], v[104:105]
	s_nop 0
	v_cvt_pk_bf16_f32 v23, v26, v27
	global_store_dword v[20:21], v23, off offset:512
	v_mov_b32_e32 v40, v100
	v_mov_b32_e32 v41, v101
	s_and_saveexec_b64 s[4:5], s[40:41]
	s_xor_b64 s[40:41], exec, s[4:5]
	s_cbranch_execz .LBB0_1003
	v_add_u32_e32 v26, 0xffffc000, v4
	v_lshrrev_b32_e32 v5, 5, v26
	s_movk_i32 s4, 0x480
	v_and_b32_e32 v23, 31, v4
	v_mul_lo_u32 v5, v5, s4
	v_or_b32_e32 v5, v5, v23
	v_add_u32_e32 v20, 0x4400, v5
	v_mov_b32_e32 v21, v183
	v_or_b32_e32 v25, 0x400, v23
	v_mov_b32_e32 v27, v183
